# fused W_o epilogue with final rmsnorm: h kept f32 in accumulators, 4-WG panel sync replaces grid barrier 5 and the P6 pass
# speedup vs baseline: 1.0212x; 1.0212x over previous
; __device__ __forceinline__ u32x2 pk4(f32x4 v) { u32x2 r; r.x = pk_bf16(v[0], v[1]); r.y = pk_bf16(v[2], v[3]); return r; }
;     __device__ __forceinline__ void operator()(const f32x4 (&acc)[2][2][4][2], const Unit& u, int wr, int wc, int fr, int fq) const {
;     ...
;                         xv[m][bj][n] = __builtin_nontemporal_load((const f32x4*)(X + (size_t)(u.pm * 256 + ai * 128 + wr * 64 + m * 16 + fr) * 1024 + u.pn * 256 + bj * 128 + wc * 32 + n * 16 + fq * 4));
; #pragma unroll
;             for (int m = 0; m < 4; ++m) {
;                 const int row = u.pm * 256 + ai * 128 + wr * 64 + m * 16 + fr; float ss = 0.f;
; #pragma unroll
;                 for (int bj = 0; bj < 2; ++bj)
; #pragma unroll
;                     for (int n = 0; n < 2; ++n) {
;                         const u32x2 hw = pk4(xv[m][bj][n] + acc[ai][bj][m][n]); const f32x4 h = unpk4(hw);
;                         ((u32x2*)HN)[native_slot(u.pm, u.pn, w4, ai, m, bj, n, lane)] = hw; ss += (h[0] * h[0] + h[1] * h[1]) + (h[2] * h[2] + h[3] * h[3]);
;                     }
;                 ss += __shfl_xor(ss, 16); ss += __shfl_xor(ss, 32);
;                 if (fq == 0) unsafeAtomicAdd(ROWSS + row, ss);
; __global__ void __launch_bounds__(512, 2) fwd_megakernel(Params p) {
;     ...
;                     rs[m] = ROWSS[pm * 256 + ai * 128 + wr * 64 + m * 16 + fr];
; #pragma unroll
;                     for (int bj = 0; bj < 2; ++bj)
; #pragma unroll
;                         for (int n = 0; n < 2; ++n) hv[m][bj][n] = ((const u32x2*)HA)[native_slot(pm, pn, w4, ai, m, bj, n, fq * 16 + fr)];
;                 }
; #pragma unroll
;                 for (int bj = 0; bj < 2; ++bj)
; #pragma unroll
;                     for (int n = 0; n < 2; ++n) gg[bj][n] = *(const f32x4*)(final_g + pn * 256 + bj * 128 + wc * 32 + n * 16 + fq * 4);
; #pragma unroll
;                 for (int m = 0; m < 4; ++m) {
;                     const float rstd = 1.0f / sqrtf(rs[m] * (1.f / 1024.f) + EPS);
; #pragma unroll
;                     for (int bj = 0; bj < 2; ++bj)
; #pragma unroll
;                         for (int n = 0; n < 2; ++n)
;                             *(f32x4*)(p.out + (size_t)(pm * 256 + ai * 128 + wr * 64 + m * 16 + fr) * 1024 + pn * 256 + bj * 128 + wc * 32 + n * 16 + fq * 4) = unpk4(hv[m][bj][n]) * rstd * gg[bj][n];
.LBB0_632:
	s_lshl_b32 s21, s38, 8
	v_add_u32_e32 v192, s21, v183
	s_lshl_b32 s28, s56, 8
	s_ashr_i32 s29, s28, 31
	v_lshl_add_u64 v[190:191], s[28:29], 2, v[184:185]
	v_and_b32_e32 v228, 0x30, v182
	s_bfe_u32 s34, s87, 0x20006
	s_lshl_b32 s34, s34, 7
	v_add_u32_e32 v228, s34, v228
	v_mov_b32_e32 v229, 0
	v_lshl_add_u64 v[230:231], s[28:29], 2, v[228:229]
	v_lshl_add_u64 v[202:203], s[22:23], 0, v[230:231]
	global_load_dwordx4 v[232:235], v[202:203], off
	global_load_dwordx4 v[236:239], v[202:203], off offset:64
	global_load_dwordx4 v[240:243], v[202:203], off offset:512
	global_load_dwordx4 v[244:247], v[202:203], off offset:576
	v_lshl_add_u64 v[248:249], s[24:25], 0, v[230:231]
	v_xor_b32_e32 v222, 16, v201
	v_lshlrev_b32_e32 v222, 2, v222
	v_xor_b32_e32 v223, 32, v201
	v_lshlrev_b32_e32 v223, 2, v223
	v_mov_b32_e32 v220, v192
	v_ashrrev_i32_e32 v221, 31, v220
	v_lshlrev_b64 v[220:221], 12, v[220:221]
	v_lshl_add_u64 v[202:203], v[190:191], 0, v[220:221]
	global_load_dwordx4 v[204:207], v[202:203], off nt
	global_load_dwordx4 v[208:211], v[202:203], off offset:64 nt
	global_load_dwordx4 v[212:215], v[202:203], off offset:512 nt
	global_load_dwordx4 v[216:219], v[202:203], off offset:576 nt
	v_add_u32_e32 v220, 16, v192
	v_ashrrev_i32_e32 v221, 31, v220
	v_lshlrev_b64 v[220:221], 12, v[220:221]
	v_lshl_add_u64 v[202:203], v[190:191], 0, v[220:221]
	global_load_dwordx4 v[172:175], v[202:203], off nt
	global_load_dwordx4 v[168:171], v[202:203], off offset:64 nt
	global_load_dwordx4 v[164:167], v[202:203], off offset:512 nt
	global_load_dwordx4 v[160:163], v[202:203], off offset:576 nt
	v_add_u32_e32 v220, 32, v192
	v_ashrrev_i32_e32 v221, 31, v220
	v_lshlrev_b64 v[220:221], 12, v[220:221]
	v_lshl_add_u64 v[202:203], v[190:191], 0, v[220:221]
	global_load_dwordx4 v[156:159], v[202:203], off nt
	global_load_dwordx4 v[152:155], v[202:203], off offset:64 nt
	global_load_dwordx4 v[148:151], v[202:203], off offset:512 nt
	global_load_dwordx4 v[144:147], v[202:203], off offset:576 nt
	v_add_u32_e32 v220, 48, v192
	v_ashrrev_i32_e32 v221, 31, v220
	v_lshlrev_b64 v[220:221], 12, v[220:221]
	v_lshl_add_u64 v[202:203], v[190:191], 0, v[220:221]
	global_load_dwordx4 v[140:143], v[202:203], off nt
	global_load_dwordx4 v[136:139], v[202:203], off offset:64 nt
	global_load_dwordx4 v[132:135], v[202:203], off offset:512 nt
	global_load_dwordx4 v[128:131], v[202:203], off offset:576 nt
	s_waitcnt vmcnt(12)
	v_pk_add_f32 v[124:125], v[124:125], v[204:205]
	v_pk_add_f32 v[126:127], v[126:127], v[206:207]
	v_pk_add_f32 v[120:121], v[120:121], v[208:209]
	v_pk_add_f32 v[122:123], v[122:123], v[210:211]
	v_pk_add_f32 v[116:117], v[116:117], v[212:213]
	v_pk_add_f32 v[118:119], v[118:119], v[214:215]
	v_pk_add_f32 v[112:113], v[112:113], v[216:217]
	v_pk_add_f32 v[114:115], v[114:115], v[218:219]
	v_mul_f32_e32 v224, v124, v124
	v_fmac_f32_e32 v224, v125, v125
	v_fmac_f32_e32 v224, v126, v126
	v_fmac_f32_e32 v224, v127, v127
	v_fmac_f32_e32 v224, v120, v120
	v_fmac_f32_e32 v224, v121, v121
	v_fmac_f32_e32 v224, v122, v122
	v_fmac_f32_e32 v224, v123, v123
	v_fmac_f32_e32 v224, v116, v116
	v_fmac_f32_e32 v224, v117, v117
	v_fmac_f32_e32 v224, v118, v118
	v_fmac_f32_e32 v224, v119, v119
	v_fmac_f32_e32 v224, v112, v112
	v_fmac_f32_e32 v224, v113, v113
	v_fmac_f32_e32 v224, v114, v114
	v_fmac_f32_e32 v224, v115, v115
	v_add_u32_e32 v220, 128, v192
	v_ashrrev_i32_e32 v221, 31, v220
	v_lshlrev_b64 v[220:221], 12, v[220:221]
	v_lshl_add_u64 v[202:203], v[190:191], 0, v[220:221]
	global_load_dwordx4 v[204:207], v[202:203], off nt
	global_load_dwordx4 v[208:211], v[202:203], off offset:64 nt
	global_load_dwordx4 v[212:215], v[202:203], off offset:512 nt
	global_load_dwordx4 v[216:219], v[202:203], off offset:576 nt
	ds_bpermute_b32 v250, v222, v224
	v_mov_b32_e32 v220, v192
	v_ashrrev_i32_e32 v221, 31, v220
	v_lshl_add_u64 v[220:221], v[220:221], 2, s[16:17]
	s_waitcnt lgkmcnt(0)
	v_add_f32_e32 v224, v224, v250
	ds_bpermute_b32 v250, v223, v224
	s_waitcnt lgkmcnt(0)
	v_add_f32_e32 v224, v224, v250
	s_mov_b64 s[34:35], exec
	s_mov_b64 exec, s[4:5]
	global_atomic_add_f32 v[220:221], v224, off
	s_mov_b64 exec, s[34:35]
	s_waitcnt vmcnt(13)
	v_pk_add_f32 v[108:109], v[108:109], v[172:173]
	v_pk_add_f32 v[110:111], v[110:111], v[174:175]
	v_pk_add_f32 v[104:105], v[104:105], v[168:169]
	v_pk_add_f32 v[106:107], v[106:107], v[170:171]
	v_pk_add_f32 v[100:101], v[100:101], v[164:165]
	v_pk_add_f32 v[102:103], v[102:103], v[166:167]
	v_pk_add_f32 v[96:97], v[96:97], v[160:161]
	v_pk_add_f32 v[98:99], v[98:99], v[162:163]
	v_mul_f32_e32 v225, v108, v108
	v_fmac_f32_e32 v225, v109, v109
	v_fmac_f32_e32 v225, v110, v110
	v_fmac_f32_e32 v225, v111, v111
	v_fmac_f32_e32 v225, v104, v104
	v_fmac_f32_e32 v225, v105, v105
	v_fmac_f32_e32 v225, v106, v106
	v_fmac_f32_e32 v225, v107, v107
	v_fmac_f32_e32 v225, v100, v100
	v_fmac_f32_e32 v225, v101, v101
	v_fmac_f32_e32 v225, v102, v102
	v_fmac_f32_e32 v225, v103, v103
	v_fmac_f32_e32 v225, v96, v96
	v_fmac_f32_e32 v225, v97, v97
	v_fmac_f32_e32 v225, v98, v98
	v_fmac_f32_e32 v225, v99, v99
	v_add_u32_e32 v220, 144, v192
	v_ashrrev_i32_e32 v221, 31, v220
	v_lshlrev_b64 v[220:221], 12, v[220:221]
	v_lshl_add_u64 v[202:203], v[190:191], 0, v[220:221]
	global_load_dwordx4 v[172:175], v[202:203], off nt
	global_load_dwordx4 v[168:171], v[202:203], off offset:64 nt
	global_load_dwordx4 v[164:167], v[202:203], off offset:512 nt
	global_load_dwordx4 v[160:163], v[202:203], off offset:576 nt
	ds_bpermute_b32 v250, v222, v225
	v_add_u32_e32 v220, 16, v192
	v_ashrrev_i32_e32 v221, 31, v220
	v_lshl_add_u64 v[220:221], v[220:221], 2, s[16:17]
	s_waitcnt lgkmcnt(0)
; __device__ __forceinline__ u32x2 pk4(f32x4 v) { u32x2 r; r.x = pk_bf16(v[0], v[1]); r.y = pk_bf16(v[2], v[3]); return r; }
; __device__ __forceinline__ f32x4 unpk4(u32x2 v) { return (f32x4){bf_lo(v.x), bf_hi(v.x), bf_lo(v.y), bf_hi(v.y)}; }
;     __device__ __forceinline__ void operator()(const f32x4 (&acc)[2][2][4][2], const Unit& u, int wr, int wc, int fr, int fq) const {
;     ...
;                         xv[m][bj][n] = __builtin_nontemporal_load((const f32x4*)(X + (size_t)(u.pm * 256 + ai * 128 + wr * 64 + m * 16 + fr) * 1024 + u.pn * 256 + bj * 128 + wc * 32 + n * 16 + fq * 4));
; #pragma unroll
;             for (int m = 0; m < 4; ++m) {
;                 const int row = u.pm * 256 + ai * 128 + wr * 64 + m * 16 + fr; float ss = 0.f;
; #pragma unroll
;                 for (int bj = 0; bj < 2; ++bj)
; #pragma unroll
;                     for (int n = 0; n < 2; ++n) {
;                         const u32x2 hw = pk4(xv[m][bj][n] + acc[ai][bj][m][n]); const f32x4 h = unpk4(hw);
;                         ((u32x2*)HN)[native_slot(u.pm, u.pn, w4, ai, m, bj, n, lane)] = hw; ss += (h[0] * h[0] + h[1] * h[1]) + (h[2] * h[2] + h[3] * h[3]);
;                     }
;                 ss += __shfl_xor(ss, 16); ss += __shfl_xor(ss, 32);
;                 if (fq == 0) unsafeAtomicAdd(ROWSS + row, ss);
	v_add_f32_e32 v225, v225, v250
	ds_bpermute_b32 v250, v223, v225
	s_waitcnt lgkmcnt(0)
	v_add_f32_e32 v225, v225, v250
	s_mov_b64 s[34:35], exec
	s_mov_b64 exec, s[4:5]
	global_atomic_add_f32 v[220:221], v225, off
	s_mov_b64 exec, s[34:35]
	s_waitcnt vmcnt(14)
	v_pk_add_f32 v[92:93], v[92:93], v[156:157]
	v_pk_add_f32 v[94:95], v[94:95], v[158:159]
	v_pk_add_f32 v[88:89], v[88:89], v[152:153]
	v_pk_add_f32 v[90:91], v[90:91], v[154:155]
	v_pk_add_f32 v[84:85], v[84:85], v[148:149]
	v_pk_add_f32 v[86:87], v[86:87], v[150:151]
	v_pk_add_f32 v[80:81], v[80:81], v[144:145]
	v_pk_add_f32 v[82:83], v[82:83], v[146:147]
	v_mul_f32_e32 v226, v92, v92
	v_fmac_f32_e32 v226, v93, v93
	v_fmac_f32_e32 v226, v94, v94
	v_fmac_f32_e32 v226, v95, v95
	v_fmac_f32_e32 v226, v88, v88
	v_fmac_f32_e32 v226, v89, v89
	v_fmac_f32_e32 v226, v90, v90
	v_fmac_f32_e32 v226, v91, v91
	v_fmac_f32_e32 v226, v84, v84
	v_fmac_f32_e32 v226, v85, v85
	v_fmac_f32_e32 v226, v86, v86
	v_fmac_f32_e32 v226, v87, v87
	v_fmac_f32_e32 v226, v80, v80
	v_fmac_f32_e32 v226, v81, v81
	v_fmac_f32_e32 v226, v82, v82
	v_fmac_f32_e32 v226, v83, v83
	v_add_u32_e32 v220, 160, v192
	v_ashrrev_i32_e32 v221, 31, v220
	v_lshlrev_b64 v[220:221], 12, v[220:221]
	v_lshl_add_u64 v[202:203], v[190:191], 0, v[220:221]
	global_load_dwordx4 v[156:159], v[202:203], off nt
	global_load_dwordx4 v[152:155], v[202:203], off offset:64 nt
	global_load_dwordx4 v[148:151], v[202:203], off offset:512 nt
	global_load_dwordx4 v[144:147], v[202:203], off offset:576 nt
	ds_bpermute_b32 v250, v222, v226
	v_add_u32_e32 v220, 32, v192
	v_ashrrev_i32_e32 v221, 31, v220
	v_lshl_add_u64 v[220:221], v[220:221], 2, s[16:17]
	s_waitcnt lgkmcnt(0)
	v_add_f32_e32 v226, v226, v250
	ds_bpermute_b32 v250, v223, v226
	s_waitcnt lgkmcnt(0)
	v_add_f32_e32 v226, v226, v250
	s_mov_b64 s[34:35], exec
	s_mov_b64 exec, s[4:5]
	global_atomic_add_f32 v[220:221], v226, off
	s_mov_b64 exec, s[34:35]
	s_waitcnt vmcnt(15)
	v_pk_add_f32 v[76:77], v[76:77], v[140:141]
	v_pk_add_f32 v[78:79], v[78:79], v[142:143]
	v_pk_add_f32 v[72:73], v[72:73], v[136:137]
	v_pk_add_f32 v[74:75], v[74:75], v[138:139]
	v_pk_add_f32 v[68:69], v[68:69], v[132:133]
	v_pk_add_f32 v[70:71], v[70:71], v[134:135]
	v_pk_add_f32 v[64:65], v[64:65], v[128:129]
	v_pk_add_f32 v[66:67], v[66:67], v[130:131]
	v_mul_f32_e32 v227, v76, v76
	v_fmac_f32_e32 v227, v77, v77
	v_fmac_f32_e32 v227, v78, v78
	v_fmac_f32_e32 v227, v79, v79
	v_fmac_f32_e32 v227, v72, v72
	v_fmac_f32_e32 v227, v73, v73
	v_fmac_f32_e32 v227, v74, v74
	v_fmac_f32_e32 v227, v75, v75
	v_fmac_f32_e32 v227, v68, v68
	v_fmac_f32_e32 v227, v69, v69
	v_fmac_f32_e32 v227, v70, v70
	v_fmac_f32_e32 v227, v71, v71
	v_fmac_f32_e32 v227, v64, v64
	v_fmac_f32_e32 v227, v65, v65
	v_fmac_f32_e32 v227, v66, v66
	v_fmac_f32_e32 v227, v67, v67
	v_add_u32_e32 v220, 176, v192
	v_ashrrev_i32_e32 v221, 31, v220
	v_lshlrev_b64 v[220:221], 12, v[220:221]
	v_lshl_add_u64 v[202:203], v[190:191], 0, v[220:221]
	global_load_dwordx4 v[140:143], v[202:203], off nt
	global_load_dwordx4 v[136:139], v[202:203], off offset:64 nt
	global_load_dwordx4 v[132:135], v[202:203], off offset:512 nt
	global_load_dwordx4 v[128:131], v[202:203], off offset:576 nt
	ds_bpermute_b32 v250, v222, v227
	v_add_u32_e32 v220, 48, v192
	v_ashrrev_i32_e32 v221, 31, v220
	v_lshl_add_u64 v[220:221], v[220:221], 2, s[16:17]
	s_waitcnt lgkmcnt(0)
	v_add_f32_e32 v227, v227, v250
	ds_bpermute_b32 v250, v223, v227
	s_waitcnt lgkmcnt(0)
	v_add_f32_e32 v227, v227, v250
	s_mov_b64 s[34:35], exec
	s_mov_b64 exec, s[4:5]
	global_atomic_add_f32 v[220:221], v227, off
	s_mov_b64 exec, s[34:35]
	s_waitcnt vmcnt(16)
	v_pk_add_f32 v[60:61], v[60:61], v[204:205]
	v_pk_add_f32 v[62:63], v[62:63], v[206:207]
	v_pk_add_f32 v[56:57], v[56:57], v[208:209]
	v_pk_add_f32 v[58:59], v[58:59], v[210:211]
	v_pk_add_f32 v[52:53], v[52:53], v[212:213]
	v_pk_add_f32 v[54:55], v[54:55], v[214:215]
	v_pk_add_f32 v[48:49], v[48:49], v[216:217]
	v_pk_add_f32 v[50:51], v[50:51], v[218:219]
	v_mul_f32_e32 v228, v60, v60
	v_fmac_f32_e32 v228, v61, v61
	v_fmac_f32_e32 v228, v62, v62
	v_fmac_f32_e32 v228, v63, v63
	v_fmac_f32_e32 v228, v56, v56
	v_fmac_f32_e32 v228, v57, v57
	v_fmac_f32_e32 v228, v58, v58
	v_fmac_f32_e32 v228, v59, v59
	v_fmac_f32_e32 v228, v52, v52
	v_fmac_f32_e32 v228, v53, v53
	v_fmac_f32_e32 v228, v54, v54
	v_fmac_f32_e32 v228, v55, v55
	v_fmac_f32_e32 v228, v48, v48
	v_fmac_f32_e32 v228, v49, v49
	v_fmac_f32_e32 v228, v50, v50
	v_fmac_f32_e32 v228, v51, v51
	ds_bpermute_b32 v250, v222, v228
	v_add_u32_e32 v220, 128, v192
	v_ashrrev_i32_e32 v221, 31, v220
	v_lshl_add_u64 v[220:221], v[220:221], 2, s[16:17]
	s_waitcnt lgkmcnt(0)
	v_add_f32_e32 v228, v228, v250
	ds_bpermute_b32 v250, v223, v228
	s_waitcnt lgkmcnt(0)
	v_add_f32_e32 v228, v228, v250
	s_mov_b64 s[34:35], exec
	s_mov_b64 exec, s[4:5]
	global_atomic_add_f32 v[220:221], v228, off
	s_mov_b64 exec, s[34:35]
	s_waitcnt vmcnt(12)
	v_pk_add_f32 v[44:45], v[44:45], v[172:173]
	v_pk_add_f32 v[46:47], v[46:47], v[174:175]
	v_pk_add_f32 v[40:41], v[40:41], v[168:169]
	v_pk_add_f32 v[42:43], v[42:43], v[170:171]
	v_pk_add_f32 v[36:37], v[36:37], v[164:165]
	v_pk_add_f32 v[38:39], v[38:39], v[166:167]
	v_pk_add_f32 v[32:33], v[32:33], v[160:161]
	v_pk_add_f32 v[34:35], v[34:35], v[162:163]
	v_mul_f32_e32 v229, v44, v44
	v_fmac_f32_e32 v229, v45, v45
	v_fmac_f32_e32 v229, v46, v46
	v_fmac_f32_e32 v229, v47, v47
	v_fmac_f32_e32 v229, v40, v40
	v_fmac_f32_e32 v229, v41, v41
	v_fmac_f32_e32 v229, v42, v42
	v_fmac_f32_e32 v229, v43, v43
	v_fmac_f32_e32 v229, v36, v36
	v_fmac_f32_e32 v229, v37, v37
	v_fmac_f32_e32 v229, v38, v38
	v_fmac_f32_e32 v229, v39, v39
	v_fmac_f32_e32 v229, v32, v32
	v_fmac_f32_e32 v229, v33, v33
	v_fmac_f32_e32 v229, v34, v34
	v_fmac_f32_e32 v229, v35, v35
	ds_bpermute_b32 v250, v222, v229
	v_add_u32_e32 v220, 144, v192
	v_ashrrev_i32_e32 v221, 31, v220
	v_lshl_add_u64 v[220:221], v[220:221], 2, s[16:17]
	s_waitcnt lgkmcnt(0)
; __device__ __forceinline__ u32x2 pk4(f32x4 v) { u32x2 r; r.x = pk_bf16(v[0], v[1]); r.y = pk_bf16(v[2], v[3]); return r; }
; __device__ __forceinline__ f32x4 unpk4(u32x2 v) { return (f32x4){bf_lo(v.x), bf_hi(v.x), bf_lo(v.y), bf_hi(v.y)}; }
;     __device__ __forceinline__ void operator()(const f32x4 (&acc)[2][2][4][2], const Unit& u, int wr, int wc, int fr, int fq) const {
;     ...
; #pragma unroll
;             for (int m = 0; m < 4; ++m) {
;                 const int row = u.pm * 256 + ai * 128 + wr * 64 + m * 16 + fr; float ss = 0.f;
; #pragma unroll
;                 for (int bj = 0; bj < 2; ++bj)
; #pragma unroll
;                     for (int n = 0; n < 2; ++n) {
;                         const u32x2 hw = pk4(xv[m][bj][n] + acc[ai][bj][m][n]); const f32x4 h = unpk4(hw);
;                         ((u32x2*)HN)[native_slot(u.pm, u.pn, w4, ai, m, bj, n, lane)] = hw; ss += (h[0] * h[0] + h[1] * h[1]) + (h[2] * h[2] + h[3] * h[3]);
;                     }
;                 ss += __shfl_xor(ss, 16); ss += __shfl_xor(ss, 32);
;                 if (fq == 0) unsafeAtomicAdd(ROWSS + row, ss);
;             }
; __global__ void __launch_bounds__(512, 2) fwd_megakernel(Params p) {
;     ...
;                     rs[m] = ROWSS[pm * 256 + ai * 128 + wr * 64 + m * 16 + fr];
; #pragma unroll
;                     for (int bj = 0; bj < 2; ++bj)
; #pragma unroll
;                         for (int n = 0; n < 2; ++n) hv[m][bj][n] = ((const u32x2*)HA)[native_slot(pm, pn, w4, ai, m, bj, n, fq * 16 + fr)];
;                 }
; #pragma unroll
;                 for (int bj = 0; bj < 2; ++bj)
; #pragma unroll
;                     for (int n = 0; n < 2; ++n) gg[bj][n] = *(const f32x4*)(final_g + pn * 256 + bj * 128 + wc * 32 + n * 16 + fq * 4);
; #pragma unroll
;                 for (int m = 0; m < 4; ++m) {
;                     const float rstd = 1.0f / sqrtf(rs[m] * (1.f / 1024.f) + EPS);
	v_add_f32_e32 v229, v229, v250
	ds_bpermute_b32 v250, v223, v229
	s_waitcnt lgkmcnt(0)
	v_add_f32_e32 v229, v229, v250
	s_mov_b64 s[34:35], exec
	s_mov_b64 exec, s[4:5]
	global_atomic_add_f32 v[220:221], v229, off
	s_mov_b64 exec, s[34:35]
	s_waitcnt vmcnt(8)
	v_pk_add_f32 v[28:29], v[28:29], v[156:157]
	v_pk_add_f32 v[30:31], v[30:31], v[158:159]
	v_pk_add_f32 v[24:25], v[24:25], v[152:153]
	v_pk_add_f32 v[26:27], v[26:27], v[154:155]
	v_pk_add_f32 v[20:21], v[20:21], v[148:149]
	v_pk_add_f32 v[22:23], v[22:23], v[150:151]
	v_pk_add_f32 v[16:17], v[16:17], v[144:145]
	v_pk_add_f32 v[18:19], v[18:19], v[146:147]
	v_mul_f32_e32 v230, v28, v28
	v_fmac_f32_e32 v230, v29, v29
	v_fmac_f32_e32 v230, v30, v30
	v_fmac_f32_e32 v230, v31, v31
	v_fmac_f32_e32 v230, v24, v24
	v_fmac_f32_e32 v230, v25, v25
	v_fmac_f32_e32 v230, v26, v26
	v_fmac_f32_e32 v230, v27, v27
	v_fmac_f32_e32 v230, v20, v20
	v_fmac_f32_e32 v230, v21, v21
	v_fmac_f32_e32 v230, v22, v22
	v_fmac_f32_e32 v230, v23, v23
	v_fmac_f32_e32 v230, v16, v16
	v_fmac_f32_e32 v230, v17, v17
	v_fmac_f32_e32 v230, v18, v18
	v_fmac_f32_e32 v230, v19, v19
	ds_bpermute_b32 v250, v222, v230
	v_add_u32_e32 v220, 160, v192
	v_ashrrev_i32_e32 v221, 31, v220
	v_lshl_add_u64 v[220:221], v[220:221], 2, s[16:17]
	s_waitcnt lgkmcnt(0)
	v_add_f32_e32 v230, v230, v250
	ds_bpermute_b32 v250, v223, v230
	s_waitcnt lgkmcnt(0)
	v_add_f32_e32 v230, v230, v250
	s_mov_b64 s[34:35], exec
	s_mov_b64 exec, s[4:5]
	global_atomic_add_f32 v[220:221], v230, off
	s_mov_b64 exec, s[34:35]
	s_waitcnt vmcnt(4)
	v_pk_add_f32 v[12:13], v[12:13], v[140:141]
	v_pk_add_f32 v[14:15], v[14:15], v[142:143]
	v_pk_add_f32 v[8:9], v[8:9], v[136:137]
	v_pk_add_f32 v[10:11], v[10:11], v[138:139]
	v_pk_add_f32 v[4:5], v[4:5], v[132:133]
	v_pk_add_f32 v[6:7], v[6:7], v[134:135]
	v_pk_add_f32 v[0:1], v[0:1], v[128:129]
	v_pk_add_f32 v[2:3], v[2:3], v[130:131]
	v_mul_f32_e32 v231, v12, v12
	v_fmac_f32_e32 v231, v13, v13
	v_fmac_f32_e32 v231, v14, v14
	v_fmac_f32_e32 v231, v15, v15
	v_fmac_f32_e32 v231, v8, v8
	v_fmac_f32_e32 v231, v9, v9
	v_fmac_f32_e32 v231, v10, v10
	v_fmac_f32_e32 v231, v11, v11
	v_fmac_f32_e32 v231, v4, v4
	v_fmac_f32_e32 v231, v5, v5
	v_fmac_f32_e32 v231, v6, v6
	v_fmac_f32_e32 v231, v7, v7
	v_fmac_f32_e32 v231, v0, v0
	v_fmac_f32_e32 v231, v1, v1
	v_fmac_f32_e32 v231, v2, v2
	v_fmac_f32_e32 v231, v3, v3
	ds_bpermute_b32 v250, v222, v231
	v_add_u32_e32 v220, 176, v192
	v_ashrrev_i32_e32 v221, 31, v220
	v_lshl_add_u64 v[220:221], v[220:221], 2, s[16:17]
	s_waitcnt lgkmcnt(0)
	v_add_f32_e32 v231, v231, v250
	ds_bpermute_b32 v250, v223, v231
	s_waitcnt lgkmcnt(0)
	v_add_f32_e32 v231, v231, v250
	s_mov_b64 s[34:35], exec
	s_mov_b64 exec, s[4:5]
	global_atomic_add_f32 v[220:221], v231, off
	s_mov_b64 exec, s[34:35]
	s_waitcnt vmcnt(0) lgkmcnt(0)
	s_barrier
	s_cmp_lg_u32 s87, 0
	s_cbranch_scc1 .Lp5f_nolead_0
	s_mov_b64 s[98:99], exec
	s_mov_b64 exec, 1
	s_lshl_b32 s100, s38, 2
	s_add_u32 s100, s100, 0x2f00000
	s_add_u32 s100, s26, s100
	s_addc_u32 s101, s27, 0
	v_mov_b32_e32 v250, 0
	v_mov_b32_e32 v251, 1
	global_atomic_add v250, v251, s[100:101]
	s_mov_b32 vcc_lo, 0
.Lp5f_spin_0:
	global_load_dword v251, v250, s[100:101] sc1
	s_waitcnt vmcnt(0)
	v_readfirstlane_b32 vcc_hi, v251
	s_nop 3
	s_cmp_ge_u32 vcc_hi, 4
	s_cbranch_scc1 .Lp5f_spun_0
	s_sleep 1
	s_add_u32 vcc_lo, vcc_lo, 1
	s_cmp_lt_u32 vcc_lo, 0x4000
	s_cbranch_scc1 .Lp5f_spin_0
.Lp5f_spun_0:
	s_mov_b64 exec, s[98:99]
.Lp5f_nolead_0:
	s_barrier
	v_mov_b32_e32 v220, v192
	v_ashrrev_i32_e32 v221, 31, v220
	v_lshl_add_u64 v[220:221], v[220:221], 2, s[16:17]
	global_load_dword v128, v[220:221], off sc0 sc1
	v_add_u32_e32 v220, 16, v192
	v_ashrrev_i32_e32 v221, 31, v220
	v_lshl_add_u64 v[220:221], v[220:221], 2, s[16:17]
	global_load_dword v130, v[220:221], off sc0 sc1
	v_add_u32_e32 v220, 32, v192
	v_ashrrev_i32_e32 v221, 31, v220
	v_lshl_add_u64 v[220:221], v[220:221], 2, s[16:17]
	global_load_dword v132, v[220:221], off sc0 sc1
	v_add_u32_e32 v220, 48, v192
	v_ashrrev_i32_e32 v221, 31, v220
	v_lshl_add_u64 v[220:221], v[220:221], 2, s[16:17]
	global_load_dword v134, v[220:221], off sc0 sc1
	v_add_u32_e32 v220, 128, v192
	v_ashrrev_i32_e32 v221, 31, v220
	v_lshl_add_u64 v[220:221], v[220:221], 2, s[16:17]
	global_load_dword v136, v[220:221], off sc0 sc1
	v_add_u32_e32 v220, 144, v192
	v_ashrrev_i32_e32 v221, 31, v220
	v_lshl_add_u64 v[220:221], v[220:221], 2, s[16:17]
	global_load_dword v138, v[220:221], off sc0 sc1
	v_add_u32_e32 v220, 160, v192
	v_ashrrev_i32_e32 v221, 31, v220
	v_lshl_add_u64 v[220:221], v[220:221], 2, s[16:17]
	global_load_dword v140, v[220:221], off sc0 sc1
	v_add_u32_e32 v220, 176, v192
	v_ashrrev_i32_e32 v221, 31, v220
	v_lshl_add_u64 v[220:221], v[220:221], 2, s[16:17]
	global_load_dword v142, v[220:221], off sc0 sc1
	v_mov_b32_e32 v144, 0x358637bd
	s_waitcnt vmcnt(0)
; __device__ __forceinline__ f32x4 unpk4(u32x2 v) { return (f32x4){bf_lo(v.x), bf_hi(v.x), bf_lo(v.y), bf_hi(v.y)}; }
; __global__ void __launch_bounds__(512, 2) fwd_megakernel(Params p) {
;     ...
;                     const float rstd = 1.0f / sqrtf(rs[m] * (1.f / 1024.f) + EPS);
; #pragma unroll
;                     for (int bj = 0; bj < 2; ++bj)
; #pragma unroll
;                         for (int n = 0; n < 2; ++n)
;                             *(f32x4*)(p.out + (size_t)(pm * 256 + ai * 128 + wr * 64 + m * 16 + fr) * 1024 + pn * 256 + bj * 128 + wc * 32 + n * 16 + fq * 4) = unpk4(hv[m][bj][n]) * rstd * gg[bj][n];
	v_fmamk_f32 v128, v128, 0x3a800000, v144
	v_fmamk_f32 v130, v130, 0x3a800000, v144
	v_fmamk_f32 v132, v132, 0x3a800000, v144
	v_fmamk_f32 v134, v134, 0x3a800000, v144
	v_fmamk_f32 v136, v136, 0x3a800000, v144
	v_fmamk_f32 v138, v138, 0x3a800000, v144
	v_fmamk_f32 v140, v140, 0x3a800000, v144
	v_fmamk_f32 v142, v142, 0x3a800000, v144
	v_rsq_f32_e32 v146, v128
	v_rsq_f32_e32 v147, v130
	v_rsq_f32_e32 v148, v132
	v_rsq_f32_e32 v149, v134
	v_rsq_f32_e32 v150, v136
	v_rsq_f32_e32 v151, v138
	v_rsq_f32_e32 v152, v140
	v_rsq_f32_e32 v153, v142
	s_nop 0
	v_mul_f32_e32 v154, v128, v146
	v_mul_f32_e32 v155, v130, v147
	v_mul_f32_e32 v156, v132, v148
	v_mul_f32_e32 v157, v134, v149
	v_mul_f32_e32 v158, v136, v150
	v_mul_f32_e32 v159, v138, v151
	v_mul_f32_e32 v160, v140, v152
	v_mul_f32_e32 v161, v142, v153
	v_mul_f32_e32 v154, v154, v146
	v_mul_f32_e32 v155, v155, v147
	v_mul_f32_e32 v156, v156, v148
	v_mul_f32_e32 v157, v157, v149
	v_mul_f32_e32 v158, v158, v150
	v_mul_f32_e32 v159, v159, v151
	v_mul_f32_e32 v160, v160, v152
	v_mul_f32_e32 v161, v161, v153
	v_mov_b32_e32 v144, 0x3fc00000
	v_fma_f32 v154, v154, -0.5, v144
	v_fma_f32 v155, v155, -0.5, v144
	v_fma_f32 v156, v156, -0.5, v144
	v_fma_f32 v157, v157, -0.5, v144
	v_fma_f32 v158, v158, -0.5, v144
	v_fma_f32 v159, v159, -0.5, v144
	v_fma_f32 v160, v160, -0.5, v144
	v_fma_f32 v161, v161, -0.5, v144
	v_mul_f32_e32 v128, v146, v154
	v_mul_f32_e32 v130, v147, v155
	v_mul_f32_e32 v132, v148, v156
	v_mul_f32_e32 v134, v149, v157
	v_mul_f32_e32 v136, v150, v158
	v_mul_f32_e32 v138, v151, v159
	v_mul_f32_e32 v140, v152, v160
	v_mul_f32_e32 v142, v153, v161
	v_mov_b32_e32 v220, v192
	v_ashrrev_i32_e32 v221, 31, v220
	v_lshlrev_b64 v[220:221], 12, v[220:221]
	v_lshl_add_u64 v[202:203], v[248:249], 0, v[220:221]
	v_pk_mul_f32 v[124:125], v[128:129], v[124:125] op_sel_hi:[0,1]
	v_pk_mul_f32 v[126:127], v[128:129], v[126:127] op_sel_hi:[0,1]
	v_pk_mul_f32 v[120:121], v[128:129], v[120:121] op_sel_hi:[0,1]
	v_pk_mul_f32 v[122:123], v[128:129], v[122:123] op_sel_hi:[0,1]
	v_pk_mul_f32 v[116:117], v[128:129], v[116:117] op_sel_hi:[0,1]
	v_pk_mul_f32 v[118:119], v[128:129], v[118:119] op_sel_hi:[0,1]
	v_pk_mul_f32 v[112:113], v[128:129], v[112:113] op_sel_hi:[0,1]
	v_pk_mul_f32 v[114:115], v[128:129], v[114:115] op_sel_hi:[0,1]
	v_pk_mul_f32 v[124:125], v[232:233], v[124:125]
	v_pk_mul_f32 v[126:127], v[234:235], v[126:127]
	v_pk_mul_f32 v[120:121], v[236:237], v[120:121]
	v_pk_mul_f32 v[122:123], v[238:239], v[122:123]
	v_pk_mul_f32 v[116:117], v[240:241], v[116:117]
	v_pk_mul_f32 v[118:119], v[242:243], v[118:119]
	v_pk_mul_f32 v[112:113], v[244:245], v[112:113]
	v_pk_mul_f32 v[114:115], v[246:247], v[114:115]
	s_nop 0
	global_store_dwordx4 v[202:203], v[124:127], off
	global_store_dwordx4 v[202:203], v[120:123], off offset:64
	global_store_dwordx4 v[202:203], v[116:119], off offset:512
	global_store_dwordx4 v[202:203], v[112:115], off offset:576
	v_add_u32_e32 v220, 16, v192
	v_ashrrev_i32_e32 v221, 31, v220
	v_lshlrev_b64 v[220:221], 12, v[220:221]
	v_lshl_add_u64 v[202:203], v[248:249], 0, v[220:221]
	v_pk_mul_f32 v[108:109], v[130:131], v[108:109] op_sel_hi:[0,1]
	v_pk_mul_f32 v[110:111], v[130:131], v[110:111] op_sel_hi:[0,1]
	v_pk_mul_f32 v[104:105], v[130:131], v[104:105] op_sel_hi:[0,1]
	v_pk_mul_f32 v[106:107], v[130:131], v[106:107] op_sel_hi:[0,1]
	v_pk_mul_f32 v[100:101], v[130:131], v[100:101] op_sel_hi:[0,1]
	v_pk_mul_f32 v[102:103], v[130:131], v[102:103] op_sel_hi:[0,1]
	v_pk_mul_f32 v[96:97], v[130:131], v[96:97] op_sel_hi:[0,1]
	v_pk_mul_f32 v[98:99], v[130:131], v[98:99] op_sel_hi:[0,1]
	v_pk_mul_f32 v[108:109], v[232:233], v[108:109]
	v_pk_mul_f32 v[110:111], v[234:235], v[110:111]
	v_pk_mul_f32 v[104:105], v[236:237], v[104:105]
	v_pk_mul_f32 v[106:107], v[238:239], v[106:107]
	v_pk_mul_f32 v[100:101], v[240:241], v[100:101]
	v_pk_mul_f32 v[102:103], v[242:243], v[102:103]
	v_pk_mul_f32 v[96:97], v[244:245], v[96:97]
	v_pk_mul_f32 v[98:99], v[246:247], v[98:99]
	s_nop 0
	global_store_dwordx4 v[202:203], v[108:111], off
	global_store_dwordx4 v[202:203], v[104:107], off offset:64
	global_store_dwordx4 v[202:203], v[100:103], off offset:512
	global_store_dwordx4 v[202:203], v[96:99], off offset:576
	v_add_u32_e32 v220, 32, v192
	v_ashrrev_i32_e32 v221, 31, v220
	v_lshlrev_b64 v[220:221], 12, v[220:221]
	v_lshl_add_u64 v[202:203], v[248:249], 0, v[220:221]
	v_pk_mul_f32 v[92:93], v[132:133], v[92:93] op_sel_hi:[0,1]
	v_pk_mul_f32 v[94:95], v[132:133], v[94:95] op_sel_hi:[0,1]
	v_pk_mul_f32 v[88:89], v[132:133], v[88:89] op_sel_hi:[0,1]
	v_pk_mul_f32 v[90:91], v[132:133], v[90:91] op_sel_hi:[0,1]
	v_pk_mul_f32 v[84:85], v[132:133], v[84:85] op_sel_hi:[0,1]
	v_pk_mul_f32 v[86:87], v[132:133], v[86:87] op_sel_hi:[0,1]
	v_pk_mul_f32 v[80:81], v[132:133], v[80:81] op_sel_hi:[0,1]
	v_pk_mul_f32 v[82:83], v[132:133], v[82:83] op_sel_hi:[0,1]
	v_pk_mul_f32 v[92:93], v[232:233], v[92:93]
	v_pk_mul_f32 v[94:95], v[234:235], v[94:95]
	v_pk_mul_f32 v[88:89], v[236:237], v[88:89]
	v_pk_mul_f32 v[90:91], v[238:239], v[90:91]
	v_pk_mul_f32 v[84:85], v[240:241], v[84:85]
	v_pk_mul_f32 v[86:87], v[242:243], v[86:87]
	v_pk_mul_f32 v[80:81], v[244:245], v[80:81]
	v_pk_mul_f32 v[82:83], v[246:247], v[82:83]
	s_nop 0
	global_store_dwordx4 v[202:203], v[92:95], off
	global_store_dwordx4 v[202:203], v[88:91], off offset:64
	global_store_dwordx4 v[202:203], v[84:87], off offset:512
	global_store_dwordx4 v[202:203], v[80:83], off offset:576
	v_add_u32_e32 v220, 48, v192
	v_ashrrev_i32_e32 v221, 31, v220
	v_lshlrev_b64 v[220:221], 12, v[220:221]
	v_lshl_add_u64 v[202:203], v[248:249], 0, v[220:221]
; #define GRID_SYNC() xcd_barrier(xb, tid_of(widx) == 0)
; __device__ __forceinline__ f32x4 unpk4(u32x2 v) { return (f32x4){bf_lo(v.x), bf_hi(v.x), bf_lo(v.y), bf_hi(v.y)}; }
; __global__ void __launch_bounds__(512, 2) fwd_megakernel(Params p) {
;     ...
;     { SchedWo S{(const char*)MERGED, (const char*)WO, G, bx}; EpiWo E{x, HA  , ROWSS}; gemm_phase(lds, 1024, 1024, 1024, S, E, widx); }
;     GRID_SYNC();
;     ...
;                             *(f32x4*)(p.out + (size_t)(pm * 256 + ai * 128 + wr * 64 + m * 16 + fr) * 1024 + pn * 256 + bj * 128 + wc * 32 + n * 16 + fq * 4) = unpk4(hv[m][bj][n]) * rstd * gg[bj][n];
	v_pk_mul_f32 v[76:77], v[134:135], v[76:77] op_sel_hi:[0,1]
	v_pk_mul_f32 v[78:79], v[134:135], v[78:79] op_sel_hi:[0,1]
	v_pk_mul_f32 v[72:73], v[134:135], v[72:73] op_sel_hi:[0,1]
	v_pk_mul_f32 v[74:75], v[134:135], v[74:75] op_sel_hi:[0,1]
	v_pk_mul_f32 v[68:69], v[134:135], v[68:69] op_sel_hi:[0,1]
	v_pk_mul_f32 v[70:71], v[134:135], v[70:71] op_sel_hi:[0,1]
	v_pk_mul_f32 v[64:65], v[134:135], v[64:65] op_sel_hi:[0,1]
	v_pk_mul_f32 v[66:67], v[134:135], v[66:67] op_sel_hi:[0,1]
	v_pk_mul_f32 v[76:77], v[232:233], v[76:77]
	v_pk_mul_f32 v[78:79], v[234:235], v[78:79]
	v_pk_mul_f32 v[72:73], v[236:237], v[72:73]
	v_pk_mul_f32 v[74:75], v[238:239], v[74:75]
	v_pk_mul_f32 v[68:69], v[240:241], v[68:69]
	v_pk_mul_f32 v[70:71], v[242:243], v[70:71]
	v_pk_mul_f32 v[64:65], v[244:245], v[64:65]
	v_pk_mul_f32 v[66:67], v[246:247], v[66:67]
	s_nop 0
	global_store_dwordx4 v[202:203], v[76:79], off
	global_store_dwordx4 v[202:203], v[72:75], off offset:64
	global_store_dwordx4 v[202:203], v[68:71], off offset:512
	global_store_dwordx4 v[202:203], v[64:67], off offset:576
	v_add_u32_e32 v220, 128, v192
	v_ashrrev_i32_e32 v221, 31, v220
	v_lshlrev_b64 v[220:221], 12, v[220:221]
	v_lshl_add_u64 v[202:203], v[248:249], 0, v[220:221]
	v_pk_mul_f32 v[60:61], v[136:137], v[60:61] op_sel_hi:[0,1]
	v_pk_mul_f32 v[62:63], v[136:137], v[62:63] op_sel_hi:[0,1]
	v_pk_mul_f32 v[56:57], v[136:137], v[56:57] op_sel_hi:[0,1]
	v_pk_mul_f32 v[58:59], v[136:137], v[58:59] op_sel_hi:[0,1]
	v_pk_mul_f32 v[52:53], v[136:137], v[52:53] op_sel_hi:[0,1]
	v_pk_mul_f32 v[54:55], v[136:137], v[54:55] op_sel_hi:[0,1]
	v_pk_mul_f32 v[48:49], v[136:137], v[48:49] op_sel_hi:[0,1]
	v_pk_mul_f32 v[50:51], v[136:137], v[50:51] op_sel_hi:[0,1]
	v_pk_mul_f32 v[60:61], v[232:233], v[60:61]
	v_pk_mul_f32 v[62:63], v[234:235], v[62:63]
	v_pk_mul_f32 v[56:57], v[236:237], v[56:57]
	v_pk_mul_f32 v[58:59], v[238:239], v[58:59]
	v_pk_mul_f32 v[52:53], v[240:241], v[52:53]
	v_pk_mul_f32 v[54:55], v[242:243], v[54:55]
	v_pk_mul_f32 v[48:49], v[244:245], v[48:49]
	v_pk_mul_f32 v[50:51], v[246:247], v[50:51]
	s_nop 0
	global_store_dwordx4 v[202:203], v[60:63], off
	global_store_dwordx4 v[202:203], v[56:59], off offset:64
	global_store_dwordx4 v[202:203], v[52:55], off offset:512
	global_store_dwordx4 v[202:203], v[48:51], off offset:576
	v_add_u32_e32 v220, 144, v192
	v_ashrrev_i32_e32 v221, 31, v220
	v_lshlrev_b64 v[220:221], 12, v[220:221]
	v_lshl_add_u64 v[202:203], v[248:249], 0, v[220:221]
	v_pk_mul_f32 v[44:45], v[138:139], v[44:45] op_sel_hi:[0,1]
	v_pk_mul_f32 v[46:47], v[138:139], v[46:47] op_sel_hi:[0,1]
	v_pk_mul_f32 v[40:41], v[138:139], v[40:41] op_sel_hi:[0,1]
	v_pk_mul_f32 v[42:43], v[138:139], v[42:43] op_sel_hi:[0,1]
	v_pk_mul_f32 v[36:37], v[138:139], v[36:37] op_sel_hi:[0,1]
	v_pk_mul_f32 v[38:39], v[138:139], v[38:39] op_sel_hi:[0,1]
	v_pk_mul_f32 v[32:33], v[138:139], v[32:33] op_sel_hi:[0,1]
	v_pk_mul_f32 v[34:35], v[138:139], v[34:35] op_sel_hi:[0,1]
	v_pk_mul_f32 v[44:45], v[232:233], v[44:45]
	v_pk_mul_f32 v[46:47], v[234:235], v[46:47]
	v_pk_mul_f32 v[40:41], v[236:237], v[40:41]
	v_pk_mul_f32 v[42:43], v[238:239], v[42:43]
	v_pk_mul_f32 v[36:37], v[240:241], v[36:37]
	v_pk_mul_f32 v[38:39], v[242:243], v[38:39]
	v_pk_mul_f32 v[32:33], v[244:245], v[32:33]
	v_pk_mul_f32 v[34:35], v[246:247], v[34:35]
	s_nop 0
	global_store_dwordx4 v[202:203], v[44:47], off
	global_store_dwordx4 v[202:203], v[40:43], off offset:64
	global_store_dwordx4 v[202:203], v[36:39], off offset:512
	global_store_dwordx4 v[202:203], v[32:35], off offset:576
	v_add_u32_e32 v220, 160, v192
	v_ashrrev_i32_e32 v221, 31, v220
	v_lshlrev_b64 v[220:221], 12, v[220:221]
	v_lshl_add_u64 v[202:203], v[248:249], 0, v[220:221]
	v_pk_mul_f32 v[28:29], v[140:141], v[28:29] op_sel_hi:[0,1]
	v_pk_mul_f32 v[30:31], v[140:141], v[30:31] op_sel_hi:[0,1]
	v_pk_mul_f32 v[24:25], v[140:141], v[24:25] op_sel_hi:[0,1]
	v_pk_mul_f32 v[26:27], v[140:141], v[26:27] op_sel_hi:[0,1]
	v_pk_mul_f32 v[20:21], v[140:141], v[20:21] op_sel_hi:[0,1]
	v_pk_mul_f32 v[22:23], v[140:141], v[22:23] op_sel_hi:[0,1]
	v_pk_mul_f32 v[16:17], v[140:141], v[16:17] op_sel_hi:[0,1]
	v_pk_mul_f32 v[18:19], v[140:141], v[18:19] op_sel_hi:[0,1]
	v_pk_mul_f32 v[28:29], v[232:233], v[28:29]
	v_pk_mul_f32 v[30:31], v[234:235], v[30:31]
	v_pk_mul_f32 v[24:25], v[236:237], v[24:25]
	v_pk_mul_f32 v[26:27], v[238:239], v[26:27]
	v_pk_mul_f32 v[20:21], v[240:241], v[20:21]
	v_pk_mul_f32 v[22:23], v[242:243], v[22:23]
	v_pk_mul_f32 v[16:17], v[244:245], v[16:17]
	v_pk_mul_f32 v[18:19], v[246:247], v[18:19]
	s_nop 0
	global_store_dwordx4 v[202:203], v[28:31], off
	global_store_dwordx4 v[202:203], v[24:27], off offset:64
	global_store_dwordx4 v[202:203], v[20:23], off offset:512
	global_store_dwordx4 v[202:203], v[16:19], off offset:576
	v_add_u32_e32 v220, 176, v192
	v_ashrrev_i32_e32 v221, 31, v220
	v_lshlrev_b64 v[220:221], 12, v[220:221]
	v_lshl_add_u64 v[202:203], v[248:249], 0, v[220:221]
	v_pk_mul_f32 v[12:13], v[142:143], v[12:13] op_sel_hi:[0,1]
	v_pk_mul_f32 v[14:15], v[142:143], v[14:15] op_sel_hi:[0,1]
	v_pk_mul_f32 v[8:9], v[142:143], v[8:9] op_sel_hi:[0,1]
	v_pk_mul_f32 v[10:11], v[142:143], v[10:11] op_sel_hi:[0,1]
	v_pk_mul_f32 v[4:5], v[142:143], v[4:5] op_sel_hi:[0,1]
	v_pk_mul_f32 v[6:7], v[142:143], v[6:7] op_sel_hi:[0,1]
	v_pk_mul_f32 v[0:1], v[142:143], v[0:1] op_sel_hi:[0,1]
	v_pk_mul_f32 v[2:3], v[142:143], v[2:3] op_sel_hi:[0,1]
	v_pk_mul_f32 v[12:13], v[232:233], v[12:13]
	v_pk_mul_f32 v[14:15], v[234:235], v[14:15]
	v_pk_mul_f32 v[8:9], v[236:237], v[8:9]
	v_pk_mul_f32 v[10:11], v[238:239], v[10:11]
	v_pk_mul_f32 v[4:5], v[240:241], v[4:5]
	v_pk_mul_f32 v[6:7], v[242:243], v[6:7]
	v_pk_mul_f32 v[0:1], v[244:245], v[0:1]
	v_pk_mul_f32 v[2:3], v[246:247], v[2:3]
	s_nop 0
	global_store_dwordx4 v[202:203], v[12:15], off
	global_store_dwordx4 v[202:203], v[8:11], off offset:64
	global_store_dwordx4 v[202:203], v[4:7], off offset:512
	global_store_dwordx4 v[202:203], v[0:3], off offset:576
	s_andn2_b64 vcc, exec, s[18:19]
	s_mov_b64 s[18:19], -1
	s_cbranch_vccnz .LBB0_621
	s_andn2_b64 vcc, exec, s[6:7]
	s_cbranch_vccnz .LBB0_620
	s_barrier
	s_branch .LBB0_620
.LBB0_651:
	s_waitcnt vmcnt(0)
	s_barrier
.LBB0_652:
	s_endpgm

; __global__ void __launch_bounds__(512, 2) fwd_megakernel(Params p) {
	.amdhsa_kernel _Z14fwd_megakernel6Params
		.amdhsa_group_segment_fixed_size 0
		.amdhsa_private_segment_fixed_size 0
		.amdhsa_kernarg_size 400
		.amdhsa_user_sgpr_count 2
		.amdhsa_user_sgpr_dispatch_ptr 0
		.amdhsa_user_sgpr_queue_ptr 0
		.amdhsa_user_sgpr_kernarg_segment_ptr 1
		.amdhsa_user_sgpr_dispatch_id 0
		.amdhsa_user_sgpr_kernarg_preload_length 0
		.amdhsa_user_sgpr_kernarg_preload_offset 0
		.amdhsa_user_sgpr_private_segment_size 0
		.amdhsa_uses_dynamic_stack 0
		.amdhsa_enable_private_segment 0
		.amdhsa_system_sgpr_workgroup_id_x 1
		.amdhsa_system_sgpr_workgroup_id_y 0
		.amdhsa_system_sgpr_workgroup_id_z 0
		.amdhsa_system_sgpr_workgroup_info 0
		.amdhsa_system_vgpr_workitem_id 0
		.amdhsa_next_free_vgpr 256
		.amdhsa_next_free_sgpr 102
		.amdhsa_accum_offset 256
		.amdhsa_reserve_vcc 1
		.amdhsa_float_round_mode_32 0
		.amdhsa_float_round_mode_16_64 0
		.amdhsa_float_denorm_mode_32 3
		.amdhsa_float_denorm_mode_16_64 3
		.amdhsa_dx10_clamp 1
		.amdhsa_ieee_mode 1
		.amdhsa_fp16_overflow 0
		.amdhsa_tg_split 0
		.amdhsa_exception_fp_ieee_invalid_op 0
		.amdhsa_exception_fp_denorm_src 0
		.amdhsa_exception_fp_ieee_div_zero 0
		.amdhsa_exception_fp_ieee_overflow 0
		.amdhsa_exception_fp_ieee_underflow 0
		.amdhsa_exception_fp_ieee_inexact 0
		.amdhsa_exception_int_div_zero 0
	.end_amdhsa_kernel

; __global__ void __launch_bounds__(512, 2) fwd_megakernel(Params p) {
amdhsa.kernels:
  - .agpr_count:     0
    .args:
      - .offset:         0
        .size:           144
        .value_kind:     by_value
      - .offset:         144
        .size:           4
        .value_kind:     hidden_block_count_x
      - .offset:         148
        .size:           4
        .value_kind:     hidden_block_count_y
      - .offset:         152
        .size:           4
        .value_kind:     hidden_block_count_z
      - .offset:         156
        .size:           2
        .value_kind:     hidden_group_size_x
      - .offset:         158
        .size:           2
        .value_kind:     hidden_group_size_y
      - .offset:         160
        .size:           2
        .value_kind:     hidden_group_size_z
      - .offset:         162
        .size:           2
        .value_kind:     hidden_remainder_x
      - .offset:         164
        .size:           2
        .value_kind:     hidden_remainder_y
      - .offset:         166
        .size:           2
        .value_kind:     hidden_remainder_z
      - .offset:         184
        .size:           8
        .value_kind:     hidden_global_offset_x
      - .offset:         192
        .size:           8
        .value_kind:     hidden_global_offset_y
      - .offset:         200
        .size:           8
        .value_kind:     hidden_global_offset_z
      - .offset:         208
        .size:           2
        .value_kind:     hidden_grid_dims
      - .offset:         264
        .size:           4
        .value_kind:     hidden_dynamic_lds_size
    .group_segment_fixed_size: 0
    .kernarg_segment_align: 8
    .kernarg_segment_size: 400
    .language:       OpenCL C
    .language_version:
      - 2
      - 0
    .max_flat_workgroup_size: 512
    .name:           _Z14fwd_megakernel6Params
    .private_segment_fixed_size: 0
    .sgpr_count:     108
    .sgpr_spill_count: 38
    .symbol:         _Z14fwd_megakernel6Params.kd
    .uniform_work_group_size: 1
    .uses_dynamic_stack: false
    .vgpr_count:     256
    .vgpr_spill_count: 0
    .wavefront_size: 64
